# channel-DFT GEMM: skip the MFMAs whose weight rows are the zero blocks of the block-diagonal DFT matrix (half of them)
# speedup vs baseline: 1.0131x; 1.0029x over previous
; #define PG8_STAGE(bufoff, gbase, voff) do { _Pragma("unroll") for (int _i = 0; _i < 2; ++_i) \
;         __builtin_amdgcn_global_load_lds((const unsigned*)((const char*)(gbase) + (voff)[_i]), (PG8_LAS unsigned*)(lds + (bufoff) + ldsw + _i * 8192), 16, 0, 0); } while (0)
; #define PG8_LDA(dst, b, h) do { _Pragma("unroll") for (int m = 0; m < 4; ++m) _Pragma("unroll") for (int k = 0; k < 2; ++k) dst[m][k] = *(const PG8_LAS bf16x8*)(lds + PG8_SA(b, h) + aoff + m * 2048 + k * 1024); } while (0)
; #define PG8_LDB(dst, b, h) do { _Pragma("unroll") for (int n = 0; n < 2; ++n) _Pragma("unroll") for (int k = 0; k < 2; ++k) dst[n][k] = *(const PG8_LAS bf16x8*)(lds + PG8_SB(b, h) + boff + n * 2048 + k * 1024); } while (0)
; #define PG8_MMA(ai, bj, At, Bt) do { __builtin_amdgcn_s_setprio(1); _Pragma("unroll") for (int m = 0; m < 4; ++m) _Pragma("unroll") for (int n = 0; n < 2; ++n) _Pragma("unroll") for (int k = 0; k < 2; ++k) \
;         acc[ai][bj][m][n] = __builtin_amdgcn_mfma_f32_16x16x32_bf16(Bt[n][k], At[m][k], acc[ai][bj][m][n], 0, 0, 0); __builtin_amdgcn_s_setprio(0); } while (0)
; #define PG8_WAIT_V(n) asm volatile("s_waitcnt vmcnt(" #n ")" ::: "memory")
; #define PG8_WAIT_L(n) asm volatile("s_waitcnt lgkmcnt(" #n ")" ::: "memory")
; #define PG8_BAR __builtin_amdgcn_s_barrier()
; #define PG8_SCHED __builtin_amdgcn_sched_barrier(0)
;     ...
;         for (int t = 0; t < nt; t += 2) {
;             const bool last = (t == nt - 2);
;             const char* a1 = cA + (size_t)(t + 1) * kstep;
;             const char* a2 = last ? nA : cA + (size_t)(t + 2) * kstep; const char* b2 = last ? nB : cB + (size_t)(t + 2) * kstep;
;             const char* a3 = a2 + kstep; const char* b3 = b2 + kstep;
;             if (last && has_next) S.a_ready(nxt);
;             if constexpr (SP2) {
;             PG8_LDB(B0, 0, 0); PG8_LDB(B1, 0, 1); PG8_SCHED; PG8_LDA(At, 0, 0); PG8_STAGE(PG8_SA(1, 1), a1 + hstepA, voffA);
;             PG8_WAIT_V(8); PG8_WAIT_L(0); PG8_BAR; PG8_MMA(0, 0, At, B0); PG8_MMA(0, 1, At, B1); PG8_BAR; PG8_SCHED;
;             PG8_LDA(At, 0, 1); PG8_STAGE(PG8_SB(0, 0), b2, voffB); PG8_STAGE(PG8_SB(0, 1), b2 + hstepB, voffB); PG8_STAGE(PG8_SA(0, 0), a2, voffA);
;             PG8_WAIT_V(8); PG8_WAIT_L(0); PG8_BAR; PG8_MMA(1, 0, At, B0); PG8_MMA(1, 1, At, B1); PG8_BAR; PG8_SCHED;
.LBB0_127:
	s_ashr_i32 s91, s90, 31
	s_lshl_b64 s[10:11], s[90:91], 19
	s_add_u32 s22, s44, s10
	s_addc_u32 s23, s45, s11
	s_lshl_b64 s[10:11], s[88:89], 9
	s_add_u32 s94, s22, s10
	s_addc_u32 s95, s23, s11
	s_andn2_b64 vcc, exec, s[72:73]
	s_cbranch_vccnz .LBB0_130
	s_and_b64 s[10:11], s[40:41], exec
	s_cselect_b32 s10, s95, s9
	s_cselect_b32 s11, s94, s8
	s_add_u32 s22, s6, 0x100
	s_addc_u32 s23, s7, 0
	s_add_u32 s6, s8, 0x40080
	s_addc_u32 s7, s9, 0
	s_mov_b32 s8, 0
	s_add_i32 s24, s8, 2
	s_add_u32 s25, s6, 0xfffc0080
	s_addc_u32 s9, s7, -1
	s_add_i32 s27, 0, 0x10000
	s_cmp_eq_u32 s18, s8
	s_cselect_b32 s9, s10, s9
	s_cselect_b32 s8, s11, s25
	v_add_u32_e32 v152, s27, v159
	s_cselect_b32 s35, s93, s23
	s_cselect_b32 s34, s92, s22
	s_add_i32 s25, 0, 0x14000
	ds_read_b128 v[144:147], v152
	ds_read_b128 v[148:151], v152 offset:1024
	ds_read_b128 v[154:157], v152 offset:2048
	ds_read_b128 v[160:163], v152 offset:3072
	v_add_u32_e32 v152, s25, v159
	ds_read_b128 v[172:175], v152
	ds_read_b128 v[180:183], v152 offset:1024
	ds_read_b128 v[184:187], v152 offset:2048
	ds_read_b128 v[188:191], v152 offset:3072
	v_lshl_add_u64 v[164:165], s[6:7], 0, v[142:143]
	s_add_i32 m0, s2, 0xc000
	ds_read_b128 v[192:195], v179
	ds_read_b128 v[196:199], v179 offset:1024
	ds_read_b128 v[200:203], v179 offset:2048
	ds_read_b128 v[204:207], v179 offset:3072
	ds_read_b128 v[208:211], v179 offset:4096
	ds_read_b128 v[212:215], v179 offset:5120
	ds_read_b128 v[216:219], v179 offset:6144
	ds_read_b128 v[220:223], v179 offset:7168
	global_load_lds_dwordx4 v[164:165], off
	v_lshl_add_u64 v[164:165], s[6:7], 0, v[140:141]
	s_add_i32 m0, s2, 0xe000
	s_nop 0
	global_load_lds_dwordx4 v[164:165], off
	s_waitcnt vmcnt(8)
	s_waitcnt lgkmcnt(0)
	s_barrier
	s_waitcnt lgkmcnt(0)
	v_mfma_f32_16x16x32_bf16 v[126:129], v[144:147], v[192:195], 0
	v_mfma_f32_16x16x32_bf16 v[122:125], v[154:157], v[192:195], 0
	v_mfma_f32_16x16x32_bf16 v[110:113], v[144:147], v[200:203], 0
	v_mfma_f32_16x16x32_bf16 v[106:109], v[154:157], v[200:203], 0
	v_mfma_f32_16x16x32_bf16 v[94:97], v[144:147], v[208:211], 0
	v_mfma_f32_16x16x32_bf16 v[90:93], v[154:157], v[208:211], 0
	v_mfma_f32_16x16x32_bf16 v[78:81], v[144:147], v[216:219], 0
	v_mfma_f32_16x16x32_bf16 v[74:77], v[154:157], v[216:219], 0
	v_mfma_f32_16x16x32_bf16 v[126:129], v[148:151], v[196:199], v[126:129]
	v_mfma_f32_16x16x32_bf16 v[122:125], v[160:163], v[196:199], v[122:125]
	v_mfma_f32_16x16x32_bf16 v[110:113], v[148:151], v[204:207], v[110:113]
	v_mfma_f32_16x16x32_bf16 v[106:109], v[160:163], v[204:207], v[106:109]
	v_mfma_f32_16x16x32_bf16 v[94:97], v[148:151], v[212:215], v[94:97]
	v_mfma_f32_16x16x32_bf16 v[90:93], v[160:163], v[212:215], v[90:93]
	v_mfma_f32_16x16x32_bf16 v[78:81], v[148:151], v[220:223], v[78:81]
	v_mfma_f32_16x16x32_bf16 v[74:77], v[160:163], v[220:223], v[74:77]
	s_barrier
	s_add_i32 s27, s27, s0
	v_lshl_add_u64 v[164:165], s[34:35], 0, v[134:135]
	s_mov_b32 m0, s27
	ds_read_b128 v[192:195], v179 offset:16384
	ds_read_b128 v[196:199], v179 offset:17408
	ds_read_b128 v[200:203], v179 offset:18432
	ds_read_b128 v[204:207], v179 offset:19456
	ds_read_b128 v[208:211], v179 offset:20480
	ds_read_b128 v[212:215], v179 offset:21504
	ds_read_b128 v[216:219], v179 offset:22528
	ds_read_b128 v[220:223], v179 offset:23552
	global_load_lds_dwordx4 v[164:165], off
	s_add_i32 m0, s27, 0x2000
	v_lshl_add_u64 v[168:169], s[34:35], 0, v[130:131]
	s_add_u32 s34, s34, s42
	s_addc_u32 s35, s35, s43
	s_add_i32 s25, s25, s0
	global_load_lds_dwordx4 v[168:169], off
	v_lshl_add_u64 v[170:171], s[34:35], 0, v[134:135]
	s_mov_b32 m0, s25
	v_lshl_add_u64 v[176:177], s[34:35], 0, v[130:131]
	global_load_lds_dwordx4 v[170:171], off
	s_add_i32 m0, s25, 0x2000
	v_lshl_add_u64 v[224:225], s[8:9], 0, v[136:137]
	global_load_lds_dwordx4 v[176:177], off
	s_mov_b32 m0, s2
	v_lshl_add_u64 v[226:227], s[8:9], 0, v[132:133]
	global_load_lds_dwordx4 v[224:225], off
	s_mov_b32 m0, s3
	s_nop 0
	global_load_lds_dwordx4 v[226:227], off
	s_waitcnt vmcnt(8)
	s_waitcnt lgkmcnt(0)
	s_barrier
	s_waitcnt lgkmcnt(0)
	v_mfma_f32_16x16x32_bf16 v[62:65], v[144:147], v[192:195], 0
	v_mfma_f32_16x16x32_bf16 v[58:61], v[154:157], v[192:195], 0
	v_mfma_f32_16x16x32_bf16 v[46:49], v[144:147], v[200:203], 0
	v_mfma_f32_16x16x32_bf16 v[42:45], v[154:157], v[200:203], 0
	v_mfma_f32_16x16x32_bf16 v[30:33], v[144:147], v[208:211], 0
	v_mfma_f32_16x16x32_bf16 v[26:29], v[154:157], v[208:211], 0
	v_mfma_f32_16x16x32_bf16 v[14:17], v[144:147], v[216:219], 0
	v_mfma_f32_16x16x32_bf16 v[10:13], v[154:157], v[216:219], 0
	v_mfma_f32_16x16x32_bf16 v[62:65], v[148:151], v[196:199], v[62:65]
	v_mfma_f32_16x16x32_bf16 v[58:61], v[160:163], v[196:199], v[58:61]
	v_mfma_f32_16x16x32_bf16 v[46:49], v[148:151], v[204:207], v[46:49]
	v_mfma_f32_16x16x32_bf16 v[42:45], v[160:163], v[204:207], v[42:45]
	v_mfma_f32_16x16x32_bf16 v[30:33], v[148:151], v[212:215], v[30:33]
	v_mfma_f32_16x16x32_bf16 v[26:29], v[160:163], v[212:215], v[26:29]
	v_mfma_f32_16x16x32_bf16 v[14:17], v[148:151], v[220:223], v[14:17]
	v_mfma_f32_16x16x32_bf16 v[10:13], v[160:163], v[220:223], v[10:13]
	s_barrier
; #define PG8_STAGE(bufoff, gbase, voff) do { _Pragma("unroll") for (int _i = 0; _i < 2; ++_i) \
;         __builtin_amdgcn_global_load_lds((const unsigned*)((const char*)(gbase) + (voff)[_i]), (PG8_LAS unsigned*)(lds + (bufoff) + ldsw + _i * 8192), 16, 0, 0); } while (0)
; #define PG8_LDA(dst, b, h) do { _Pragma("unroll") for (int m = 0; m < 4; ++m) _Pragma("unroll") for (int k = 0; k < 2; ++k) dst[m][k] = *(const PG8_LAS bf16x8*)(lds + PG8_SA(b, h) + aoff + m * 2048 + k * 1024); } while (0)
; #define PG8_LDB(dst, b, h) do { _Pragma("unroll") for (int n = 0; n < 2; ++n) _Pragma("unroll") for (int k = 0; k < 2; ++k) dst[n][k] = *(const PG8_LAS bf16x8*)(lds + PG8_SB(b, h) + boff + n * 2048 + k * 1024); } while (0)
; #define PG8_MMA(ai, bj, At, Bt) do { __builtin_amdgcn_s_setprio(1); _Pragma("unroll") for (int m = 0; m < 4; ++m) _Pragma("unroll") for (int n = 0; n < 2; ++n) _Pragma("unroll") for (int k = 0; k < 2; ++k) \
;         acc[ai][bj][m][n] = __builtin_amdgcn_mfma_f32_16x16x32_bf16(Bt[n][k], At[m][k], acc[ai][bj][m][n], 0, 0, 0); __builtin_amdgcn_s_setprio(0); } while (0)
; #define PG8_WAIT_V(n) asm volatile("s_waitcnt vmcnt(" #n ")" ::: "memory")
; #define PG8_WAIT_L(n) asm volatile("s_waitcnt lgkmcnt(" #n ")" ::: "memory")
; #define PG8_BAR __builtin_amdgcn_s_barrier()
; #define PG8_SCHED __builtin_amdgcn_sched_barrier(0)
;     ...
;             PG8_LDB(B0, 1, 0); PG8_LDB(B1, 1, 1); PG8_SCHED; PG8_LDA(At, 1, 0); PG8_STAGE(PG8_SA(0, 1), a2 + hstepA, voffA);
;             PG8_WAIT_V(8); PG8_WAIT_L(0); PG8_BAR; PG8_MMA(0, 0, At, B0); PG8_MMA(0, 1, At, B1); PG8_BAR; PG8_SCHED;
;             PG8_LDA(At, 1, 1); PG8_STAGE(PG8_SB(1, 0), b3, voffB); PG8_STAGE(PG8_SB(1, 1), b3 + hstepB, voffB); PG8_STAGE(PG8_SA(1, 0), a3, voffA);
;             PG8_WAIT_V(8); PG8_WAIT_L(0); PG8_BAR; PG8_MMA(1, 0, At, B0); PG8_MMA(1, 1, At, B1); PG8_BAR; PG8_SCHED;
	s_add_i32 s25, 0, 0x18000
	v_add_u32_e32 v152, s25, v159
	s_add_i32 s27, 0, 0x1c000
	ds_read_b128 v[144:147], v152
	ds_read_b128 v[148:151], v152 offset:1024
	ds_read_b128 v[154:157], v152 offset:2048
	ds_read_b128 v[160:163], v152 offset:3072
	v_add_u32_e32 v152, s27, v159
	ds_read_b128 v[172:175], v152
	ds_read_b128 v[180:183], v152 offset:1024
	ds_read_b128 v[184:187], v152 offset:2048
	ds_read_b128 v[188:191], v152 offset:3072
	s_add_u32 s8, s8, 0x40000
	s_addc_u32 s9, s9, 0
	s_mov_b32 m0, s12
	v_lshl_add_u64 v[228:229], s[8:9], 0, v[136:137]
	ds_read_b128 v[192:195], v179 offset:32768
	ds_read_b128 v[196:199], v179 offset:33792
	ds_read_b128 v[200:203], v179 offset:34816
	ds_read_b128 v[204:207], v179 offset:35840
	ds_read_b128 v[208:211], v179 offset:36864
	ds_read_b128 v[212:215], v179 offset:37888
	ds_read_b128 v[216:219], v179 offset:38912
	ds_read_b128 v[220:223], v179 offset:39936
	global_load_lds_dwordx4 v[228:229], off
	v_lshl_add_u64 v[228:229], s[8:9], 0, v[132:133]
	s_mov_b32 m0, s13
	s_nop 0
	global_load_lds_dwordx4 v[228:229], off
	s_waitcnt vmcnt(8)
	s_waitcnt lgkmcnt(0)
	s_barrier
	s_waitcnt lgkmcnt(0)
	v_mfma_f32_16x16x32_bf16 v[126:129], v[144:147], v[192:195], v[126:129]
	v_mfma_f32_16x16x32_bf16 v[122:125], v[154:157], v[192:195], v[122:125]
	v_mfma_f32_16x16x32_bf16 v[110:113], v[144:147], v[200:203], v[110:113]
	v_mfma_f32_16x16x32_bf16 v[106:109], v[154:157], v[200:203], v[106:109]
	v_mfma_f32_16x16x32_bf16 v[94:97], v[144:147], v[208:211], v[94:97]
	v_mfma_f32_16x16x32_bf16 v[90:93], v[154:157], v[208:211], v[90:93]
	v_mfma_f32_16x16x32_bf16 v[78:81], v[144:147], v[216:219], v[78:81]
	v_mfma_f32_16x16x32_bf16 v[74:77], v[154:157], v[216:219], v[74:77]
	v_mfma_f32_16x16x32_bf16 v[126:129], v[148:151], v[196:199], v[126:129]
	v_mfma_f32_16x16x32_bf16 v[122:125], v[160:163], v[196:199], v[122:125]
	v_mfma_f32_16x16x32_bf16 v[110:113], v[148:151], v[204:207], v[110:113]
	v_mfma_f32_16x16x32_bf16 v[106:109], v[160:163], v[204:207], v[106:109]
	v_mfma_f32_16x16x32_bf16 v[94:97], v[148:151], v[212:215], v[94:97]
	v_mfma_f32_16x16x32_bf16 v[90:93], v[160:163], v[212:215], v[90:93]
	v_mfma_f32_16x16x32_bf16 v[78:81], v[148:151], v[220:223], v[78:81]
	v_mfma_f32_16x16x32_bf16 v[74:77], v[160:163], v[220:223], v[74:77]
	s_barrier
	s_add_i32 s8, s25, s0
	v_lshl_add_u64 v[164:165], v[164:165], 0, s[62:63]
	s_mov_b32 m0, s8
	ds_read_b128 v[192:195], v179 offset:49152
	ds_read_b128 v[196:199], v179 offset:50176
	ds_read_b128 v[200:203], v179 offset:51200
	ds_read_b128 v[204:207], v179 offset:52224
	ds_read_b128 v[208:211], v179 offset:53248
	ds_read_b128 v[212:215], v179 offset:54272
	ds_read_b128 v[216:219], v179 offset:55296
	ds_read_b128 v[220:223], v179 offset:56320
	global_load_lds_dwordx4 v[164:165], off
	v_lshl_add_u64 v[164:165], v[168:169], 0, s[62:63]
	s_add_i32 m0, s8, 0x2000
	s_add_i32 s8, s27, s0
	global_load_lds_dwordx4 v[164:165], off
	v_lshl_add_u64 v[164:165], v[170:171], 0, s[62:63]
	s_mov_b32 m0, s8
	s_nop 0
	global_load_lds_dwordx4 v[164:165], off
	v_lshl_add_u64 v[164:165], v[176:177], 0, s[62:63]
	s_add_i32 m0, s8, 0x2000
	s_nop 0
	global_load_lds_dwordx4 v[164:165], off
	v_lshl_add_u64 v[164:165], v[224:225], 0, s[62:63]
	s_mov_b32 m0, s16
	s_nop 0
	global_load_lds_dwordx4 v[164:165], off
	v_lshl_add_u64 v[164:165], v[226:227], 0, s[62:63]
	s_mov_b32 m0, s17
	s_nop 0
	global_load_lds_dwordx4 v[164:165], off
	s_waitcnt vmcnt(8)
	s_waitcnt lgkmcnt(0)
	s_barrier
	s_waitcnt lgkmcnt(0)
	v_mfma_f32_16x16x32_bf16 v[62:65], v[144:147], v[192:195], v[62:65]
	v_mfma_f32_16x16x32_bf16 v[58:61], v[154:157], v[192:195], v[58:61]
	v_mfma_f32_16x16x32_bf16 v[46:49], v[144:147], v[200:203], v[46:49]
	v_mfma_f32_16x16x32_bf16 v[42:45], v[154:157], v[200:203], v[42:45]
	v_mfma_f32_16x16x32_bf16 v[30:33], v[144:147], v[208:211], v[30:33]
	v_mfma_f32_16x16x32_bf16 v[26:29], v[154:157], v[208:211], v[26:29]
	v_mfma_f32_16x16x32_bf16 v[14:17], v[144:147], v[216:219], v[14:17]
	v_mfma_f32_16x16x32_bf16 v[10:13], v[154:157], v[216:219], v[10:13]
	v_mfma_f32_16x16x32_bf16 v[62:65], v[148:151], v[196:199], v[62:65]
	v_mfma_f32_16x16x32_bf16 v[58:61], v[160:163], v[196:199], v[58:61]
	v_mfma_f32_16x16x32_bf16 v[46:49], v[148:151], v[204:207], v[46:49]
	v_mfma_f32_16x16x32_bf16 v[42:45], v[160:163], v[204:207], v[42:45]
	v_mfma_f32_16x16x32_bf16 v[30:33], v[148:151], v[212:215], v[30:33]
	v_mfma_f32_16x16x32_bf16 v[26:29], v[160:163], v[212:215], v[26:29]
	v_mfma_f32_16x16x32_bf16 v[14:17], v[148:151], v[220:223], v[14:17]
	v_mfma_f32_16x16x32_bf16 v[10:13], v[160:163], v[220:223], v[10:13]
	s_barrier
	s_add_u32 s22, s22, 0x100
	s_addc_u32 s23, s23, 0
	s_add_u32 s6, s6, 0x100
	s_addc_u32 s7, s7, 0
	s_cmp_ge_i32 s24, s14
	s_mov_b32 s8, s24
	s_cbranch_scc1 .LBB0_130
; #define PG8_STAGE(bufoff, gbase, voff) do { _Pragma("unroll") for (int _i = 0; _i < 2; ++_i) \
;         __builtin_amdgcn_global_load_lds((const unsigned*)((const char*)(gbase) + (voff)[_i]), (PG8_LAS unsigned*)(lds + (bufoff) + ldsw + _i * 8192), 16, 0, 0); } while (0)
; #define PG8_LDA(dst, b, h) do { _Pragma("unroll") for (int m = 0; m < 4; ++m) _Pragma("unroll") for (int k = 0; k < 2; ++k) dst[m][k] = *(const PG8_LAS bf16x8*)(lds + PG8_SA(b, h) + aoff + m * 2048 + k * 1024); } while (0)
; #define PG8_WAIT_V(n) asm volatile("s_waitcnt vmcnt(" #n ")" ::: "memory")
; #define PG8_WAIT_L(n) asm volatile("s_waitcnt lgkmcnt(" #n ")" ::: "memory")
;     ...
;         const bool has_next = S.next(ui + 1, nxt);
;         const char* nA = has_next ? (const char*)gA + (size_t)nxt.pm * tstepA + (size_t)nxt.pn * acolB : cA; const char* nB = has_next ? (const char*)gB + (size_t)nxt.pn * tstepB : cB;
;         for (int t = 0; t < nt; t += 2) {
;             const bool last = (t == nt - 2);
;             const char* a1 = cA + (size_t)(t + 1) * kstep;
;             const char* a2 = last ? nA : cA + (size_t)(t + 2) * kstep; const char* b2 = last ? nB : cB + (size_t)(t + 2) * kstep;
;             const char* a3 = a2 + kstep; const char* b3 = b2 + kstep;
;             if (last && has_next) S.a_ready(nxt);
;             if constexpr (SP2) {
;             PG8_LDB(B0, 0, 0); PG8_LDB(B1, 0, 1); PG8_SCHED; PG8_LDA(At, 0, 0); PG8_STAGE(PG8_SA(1, 1), a1 + hstepA, voffA);
;             PG8_WAIT_V(8); PG8_WAIT_L(0); PG8_BAR; PG8_MMA(0, 0, At, B0); PG8_MMA(0, 1, At, B1); PG8_BAR; PG8_SCHED;
;             PG8_LDA(At, 0, 1); PG8_STAGE(PG8_SB(0, 0), b2, voffB); PG8_STAGE(PG8_SB(0, 1), b2 + hstepB, voffB); PG8_STAGE(PG8_SA(0, 0), a2, voffA);
;             PG8_WAIT_V(8); PG8_WAIT_L(0); PG8_BAR; PG8_MMA(1, 0, At, B0); PG8_MMA(1, 1, At, B1); PG8_BAR; PG8_SCHED;
;             PG8_LDB(B0, 1, 0); PG8_LDB(B1, 1, 1); PG8_SCHED; PG8_LDA(At, 1, 0); PG8_STAGE(PG8_SA(0, 1), a2 + hstepA, voffA);
;             PG8_WAIT_V(8); PG8_WAIT_L(0); PG8_BAR; PG8_MMA(0, 0, At, B0); PG8_MMA(0, 1, At, B1); PG8_BAR; PG8_SCHED;
;             PG8_LDA(At, 1, 1); PG8_STAGE(PG8_SB(1, 0), b3, voffB); PG8_STAGE(PG8_SB(1, 1), b3 + hstepB, voffB); PG8_STAGE(PG8_SA(1, 0), a3, voffA);
;             PG8_WAIT_V(8); PG8_WAIT_L(0); PG8_BAR; PG8_MMA(1, 0, At, B0); PG8_MMA(1, 1, At, B1); PG8_BAR; PG8_SCHED;
.LBB0_129:
	s_add_i32 s24, s8, 2
	s_add_u32 s25, s6, 0xfffc0080
	s_addc_u32 s9, s7, -1
	s_add_i32 s27, 0, 0x10000
	s_cmp_eq_u32 s18, s8
	s_cselect_b32 s9, s10, s9
	s_cselect_b32 s8, s11, s25
	v_add_u32_e32 v152, s27, v159
	s_cselect_b32 s35, s93, s23
	s_cselect_b32 s34, s92, s22
	s_add_i32 s25, 0, 0x14000
	ds_read_b128 v[144:147], v152
	ds_read_b128 v[148:151], v152 offset:1024
	ds_read_b128 v[154:157], v152 offset:2048
	ds_read_b128 v[160:163], v152 offset:3072
	v_add_u32_e32 v152, s25, v159
	ds_read_b128 v[172:175], v152
	ds_read_b128 v[180:183], v152 offset:1024
	ds_read_b128 v[184:187], v152 offset:2048
	ds_read_b128 v[188:191], v152 offset:3072
	v_lshl_add_u64 v[164:165], s[6:7], 0, v[142:143]
	s_add_i32 m0, s2, 0xc000
	ds_read_b128 v[192:195], v179
	ds_read_b128 v[196:199], v179 offset:1024
	ds_read_b128 v[200:203], v179 offset:2048
	ds_read_b128 v[204:207], v179 offset:3072
	ds_read_b128 v[208:211], v179 offset:4096
	ds_read_b128 v[212:215], v179 offset:5120
	ds_read_b128 v[216:219], v179 offset:6144
	ds_read_b128 v[220:223], v179 offset:7168
	global_load_lds_dwordx4 v[164:165], off
	v_lshl_add_u64 v[164:165], s[6:7], 0, v[140:141]
	s_add_i32 m0, s2, 0xe000
	s_nop 0
	global_load_lds_dwordx4 v[164:165], off
	s_waitcnt vmcnt(8)
	s_waitcnt lgkmcnt(0)
	s_barrier
	s_waitcnt lgkmcnt(0)
	v_mfma_f32_16x16x32_bf16 v[118:121], v[172:175], v[192:195], 0
	v_mfma_f32_16x16x32_bf16 v[114:117], v[184:187], v[192:195], 0
	v_mfma_f32_16x16x32_bf16 v[102:105], v[172:175], v[200:203], 0
	v_mfma_f32_16x16x32_bf16 v[98:101], v[184:187], v[200:203], 0
	v_mfma_f32_16x16x32_bf16 v[86:89], v[172:175], v[208:211], 0
	v_mfma_f32_16x16x32_bf16 v[82:85], v[184:187], v[208:211], 0
	v_mfma_f32_16x16x32_bf16 v[70:73], v[172:175], v[216:219], 0
	v_mfma_f32_16x16x32_bf16 v[66:69], v[184:187], v[216:219], 0
	v_mfma_f32_16x16x32_bf16 v[118:121], v[180:183], v[196:199], v[118:121]
	v_mfma_f32_16x16x32_bf16 v[114:117], v[188:191], v[196:199], v[114:117]
	v_mfma_f32_16x16x32_bf16 v[102:105], v[180:183], v[204:207], v[102:105]
	v_mfma_f32_16x16x32_bf16 v[98:101], v[188:191], v[204:207], v[98:101]
	v_mfma_f32_16x16x32_bf16 v[86:89], v[180:183], v[212:215], v[86:89]
	v_mfma_f32_16x16x32_bf16 v[82:85], v[188:191], v[212:215], v[82:85]
	v_mfma_f32_16x16x32_bf16 v[70:73], v[180:183], v[220:223], v[70:73]
	v_mfma_f32_16x16x32_bf16 v[66:69], v[188:191], v[220:223], v[66:69]
	s_barrier
	s_add_i32 s27, s27, s0
	v_lshl_add_u64 v[164:165], s[34:35], 0, v[134:135]
	s_mov_b32 m0, s27
	ds_read_b128 v[192:195], v179 offset:16384
	ds_read_b128 v[196:199], v179 offset:17408
	ds_read_b128 v[200:203], v179 offset:18432
	ds_read_b128 v[204:207], v179 offset:19456
	ds_read_b128 v[208:211], v179 offset:20480
	ds_read_b128 v[212:215], v179 offset:21504
	ds_read_b128 v[216:219], v179 offset:22528
	ds_read_b128 v[220:223], v179 offset:23552
	global_load_lds_dwordx4 v[164:165], off
	s_add_i32 m0, s27, 0x2000
	v_lshl_add_u64 v[168:169], s[34:35], 0, v[130:131]
	s_add_u32 s34, s34, s42
	s_addc_u32 s35, s35, s43
	s_add_i32 s25, s25, s0
	global_load_lds_dwordx4 v[168:169], off
	v_lshl_add_u64 v[170:171], s[34:35], 0, v[134:135]
	s_mov_b32 m0, s25
	v_lshl_add_u64 v[176:177], s[34:35], 0, v[130:131]
	global_load_lds_dwordx4 v[170:171], off
	s_add_i32 m0, s25, 0x2000
	v_lshl_add_u64 v[224:225], s[8:9], 0, v[136:137]
	global_load_lds_dwordx4 v[176:177], off
	s_mov_b32 m0, s2
	v_lshl_add_u64 v[226:227], s[8:9], 0, v[132:133]
	global_load_lds_dwordx4 v[224:225], off
	s_mov_b32 m0, s3
	s_nop 0
	global_load_lds_dwordx4 v[226:227], off
	s_waitcnt vmcnt(8)
	s_waitcnt lgkmcnt(0)
	s_barrier
	s_waitcnt lgkmcnt(0)
	v_mfma_f32_16x16x32_bf16 v[54:57], v[172:175], v[192:195], 0
	v_mfma_f32_16x16x32_bf16 v[50:53], v[184:187], v[192:195], 0
	v_mfma_f32_16x16x32_bf16 v[38:41], v[172:175], v[200:203], 0
	v_mfma_f32_16x16x32_bf16 v[34:37], v[184:187], v[200:203], 0
	v_mfma_f32_16x16x32_bf16 v[22:25], v[172:175], v[208:211], 0
	v_mfma_f32_16x16x32_bf16 v[18:21], v[184:187], v[208:211], 0
	v_mfma_f32_16x16x32_bf16 v[6:9], v[172:175], v[216:219], 0
	v_mfma_f32_16x16x32_bf16 v[2:5], v[184:187], v[216:219], 0
	v_mfma_f32_16x16x32_bf16 v[54:57], v[180:183], v[196:199], v[54:57]
	v_mfma_f32_16x16x32_bf16 v[50:53], v[188:191], v[196:199], v[50:53]
	v_mfma_f32_16x16x32_bf16 v[38:41], v[180:183], v[204:207], v[38:41]
	v_mfma_f32_16x16x32_bf16 v[34:37], v[188:191], v[204:207], v[34:37]
	v_mfma_f32_16x16x32_bf16 v[22:25], v[180:183], v[212:215], v[22:25]
	v_mfma_f32_16x16x32_bf16 v[18:21], v[188:191], v[212:215], v[18:21]
	v_mfma_f32_16x16x32_bf16 v[6:9], v[180:183], v[220:223], v[6:9]
	v_mfma_f32_16x16x32_bf16 v[2:5], v[188:191], v[220:223], v[2:5]
	s_barrier
; #define PG8_STAGE(bufoff, gbase, voff) do { _Pragma("unroll") for (int _i = 0; _i < 2; ++_i) \
;         __builtin_amdgcn_global_load_lds((const unsigned*)((const char*)(gbase) + (voff)[_i]), (PG8_LAS unsigned*)(lds + (bufoff) + ldsw + _i * 8192), 16, 0, 0); } while (0)
; #define PG8_LDA(dst, b, h) do { _Pragma("unroll") for (int m = 0; m < 4; ++m) _Pragma("unroll") for (int k = 0; k < 2; ++k) dst[m][k] = *(const PG8_LAS bf16x8*)(lds + PG8_SA(b, h) + aoff + m * 2048 + k * 1024); } while (0)
; #define PG8_LDB(dst, b, h) do { _Pragma("unroll") for (int n = 0; n < 2; ++n) _Pragma("unroll") for (int k = 0; k < 2; ++k) dst[n][k] = *(const PG8_LAS bf16x8*)(lds + PG8_SB(b, h) + boff + n * 2048 + k * 1024); } while (0)
; #define PG8_MMA(ai, bj, At, Bt) do { __builtin_amdgcn_s_setprio(1); _Pragma("unroll") for (int m = 0; m < 4; ++m) _Pragma("unroll") for (int n = 0; n < 2; ++n) _Pragma("unroll") for (int k = 0; k < 2; ++k) \
;         acc[ai][bj][m][n] = __builtin_amdgcn_mfma_f32_16x16x32_bf16(Bt[n][k], At[m][k], acc[ai][bj][m][n], 0, 0, 0); __builtin_amdgcn_s_setprio(0); } while (0)
; #define PG8_WAIT_V(n) asm volatile("s_waitcnt vmcnt(" #n ")" ::: "memory")
; #define PG8_WAIT_L(n) asm volatile("s_waitcnt lgkmcnt(" #n ")" ::: "memory")
; #define PG8_BAR __builtin_amdgcn_s_barrier()
; #define PG8_SCHED __builtin_amdgcn_sched_barrier(0)
;     ...
;             PG8_LDB(B0, 0, 0); PG8_LDB(B1, 0, 1); PG8_SCHED; PG8_LDA(At, 0, 0); PG8_STAGE(PG8_SA(1, 1), a1 + hstepA, voffA);
;             PG8_WAIT_V(8); PG8_WAIT_L(0); PG8_BAR; PG8_MMA(0, 0, At, B0); PG8_MMA(0, 1, At, B1); PG8_BAR; PG8_SCHED;
;             PG8_LDA(At, 0, 1); PG8_STAGE(PG8_SB(0, 0), b2, voffB); PG8_STAGE(PG8_SB(0, 1), b2 + hstepB, voffB); PG8_STAGE(PG8_SA(0, 0), a2, voffA);
;             PG8_WAIT_V(8); PG8_WAIT_L(0); PG8_BAR; PG8_MMA(1, 0, At, B0); PG8_MMA(1, 1, At, B1); PG8_BAR; PG8_SCHED;
;             PG8_LDB(B0, 1, 0); PG8_LDB(B1, 1, 1); PG8_SCHED; PG8_LDA(At, 1, 0); PG8_STAGE(PG8_SA(0, 1), a2 + hstepA, voffA);
;             PG8_WAIT_V(8); PG8_WAIT_L(0); PG8_BAR; PG8_MMA(0, 0, At, B0); PG8_MMA(0, 1, At, B1); PG8_BAR; PG8_SCHED;
;             PG8_LDA(At, 1, 1); PG8_STAGE(PG8_SB(1, 0), b3, voffB); PG8_STAGE(PG8_SB(1, 1), b3 + hstepB, voffB); PG8_STAGE(PG8_SA(1, 0), a3, voffA);
;             PG8_WAIT_V(8); PG8_WAIT_L(0); PG8_BAR; PG8_MMA(1, 0, At, B0); PG8_MMA(1, 1, At, B1); PG8_BAR; PG8_SCHED;
	s_add_i32 s25, 0, 0x18000
	v_add_u32_e32 v152, s25, v159
	s_add_i32 s27, 0, 0x1c000
	ds_read_b128 v[144:147], v152
	ds_read_b128 v[148:151], v152 offset:1024
	ds_read_b128 v[154:157], v152 offset:2048
	ds_read_b128 v[160:163], v152 offset:3072
	v_add_u32_e32 v152, s27, v159
	ds_read_b128 v[172:175], v152
	ds_read_b128 v[180:183], v152 offset:1024
	ds_read_b128 v[184:187], v152 offset:2048
	ds_read_b128 v[188:191], v152 offset:3072
	s_add_u32 s8, s8, 0x40000
	s_addc_u32 s9, s9, 0
	s_mov_b32 m0, s12
	v_lshl_add_u64 v[228:229], s[8:9], 0, v[136:137]
	ds_read_b128 v[192:195], v179 offset:32768
	ds_read_b128 v[196:199], v179 offset:33792
	ds_read_b128 v[200:203], v179 offset:34816
	ds_read_b128 v[204:207], v179 offset:35840
	ds_read_b128 v[208:211], v179 offset:36864
	ds_read_b128 v[212:215], v179 offset:37888
	ds_read_b128 v[216:219], v179 offset:38912
	ds_read_b128 v[220:223], v179 offset:39936
	global_load_lds_dwordx4 v[228:229], off
	v_lshl_add_u64 v[228:229], s[8:9], 0, v[132:133]
	s_mov_b32 m0, s13
	s_nop 0
	global_load_lds_dwordx4 v[228:229], off
	s_waitcnt vmcnt(8)
	s_waitcnt lgkmcnt(0)
	s_barrier
	s_waitcnt lgkmcnt(0)
	v_mfma_f32_16x16x32_bf16 v[118:121], v[172:175], v[192:195], v[118:121]
	v_mfma_f32_16x16x32_bf16 v[114:117], v[184:187], v[192:195], v[114:117]
	v_mfma_f32_16x16x32_bf16 v[102:105], v[172:175], v[200:203], v[102:105]
	v_mfma_f32_16x16x32_bf16 v[98:101], v[184:187], v[200:203], v[98:101]
	v_mfma_f32_16x16x32_bf16 v[86:89], v[172:175], v[208:211], v[86:89]
	v_mfma_f32_16x16x32_bf16 v[82:85], v[184:187], v[208:211], v[82:85]
	v_mfma_f32_16x16x32_bf16 v[70:73], v[172:175], v[216:219], v[70:73]
	v_mfma_f32_16x16x32_bf16 v[66:69], v[184:187], v[216:219], v[66:69]
	v_mfma_f32_16x16x32_bf16 v[118:121], v[180:183], v[196:199], v[118:121]
	v_mfma_f32_16x16x32_bf16 v[114:117], v[188:191], v[196:199], v[114:117]
	v_mfma_f32_16x16x32_bf16 v[102:105], v[180:183], v[204:207], v[102:105]
	v_mfma_f32_16x16x32_bf16 v[98:101], v[188:191], v[204:207], v[98:101]
	v_mfma_f32_16x16x32_bf16 v[86:89], v[180:183], v[212:215], v[86:89]
	v_mfma_f32_16x16x32_bf16 v[82:85], v[188:191], v[212:215], v[82:85]
	v_mfma_f32_16x16x32_bf16 v[70:73], v[180:183], v[220:223], v[70:73]
	v_mfma_f32_16x16x32_bf16 v[66:69], v[188:191], v[220:223], v[66:69]
	s_barrier
	s_add_i32 s8, s25, s0
	v_lshl_add_u64 v[164:165], v[164:165], 0, s[62:63]
	s_mov_b32 m0, s8
	ds_read_b128 v[192:195], v179 offset:49152
	ds_read_b128 v[196:199], v179 offset:50176
	ds_read_b128 v[200:203], v179 offset:51200
	ds_read_b128 v[204:207], v179 offset:52224
	ds_read_b128 v[208:211], v179 offset:53248
	ds_read_b128 v[212:215], v179 offset:54272
	ds_read_b128 v[216:219], v179 offset:55296
	ds_read_b128 v[220:223], v179 offset:56320
	global_load_lds_dwordx4 v[164:165], off
	v_lshl_add_u64 v[164:165], v[168:169], 0, s[62:63]
	s_add_i32 m0, s8, 0x2000
	s_add_i32 s8, s27, s0
	global_load_lds_dwordx4 v[164:165], off
	v_lshl_add_u64 v[164:165], v[170:171], 0, s[62:63]
	s_mov_b32 m0, s8
	s_nop 0
	global_load_lds_dwordx4 v[164:165], off
	v_lshl_add_u64 v[164:165], v[176:177], 0, s[62:63]
	s_add_i32 m0, s8, 0x2000
	s_nop 0
	global_load_lds_dwordx4 v[164:165], off
	v_lshl_add_u64 v[164:165], v[224:225], 0, s[62:63]
	s_mov_b32 m0, s16
	s_nop 0
	global_load_lds_dwordx4 v[164:165], off
	v_lshl_add_u64 v[164:165], v[226:227], 0, s[62:63]
	s_mov_b32 m0, s17
	s_nop 0
	global_load_lds_dwordx4 v[164:165], off
	s_waitcnt vmcnt(8)
	s_waitcnt lgkmcnt(0)
	s_barrier
	s_waitcnt lgkmcnt(0)
	v_mfma_f32_16x16x32_bf16 v[54:57], v[172:175], v[192:195], v[54:57]
	v_mfma_f32_16x16x32_bf16 v[50:53], v[184:187], v[192:195], v[50:53]
	v_mfma_f32_16x16x32_bf16 v[38:41], v[172:175], v[200:203], v[38:41]
	v_mfma_f32_16x16x32_bf16 v[34:37], v[184:187], v[200:203], v[34:37]
	v_mfma_f32_16x16x32_bf16 v[22:25], v[172:175], v[208:211], v[22:25]
	v_mfma_f32_16x16x32_bf16 v[18:21], v[184:187], v[208:211], v[18:21]
	v_mfma_f32_16x16x32_bf16 v[6:9], v[172:175], v[216:219], v[6:9]
	v_mfma_f32_16x16x32_bf16 v[2:5], v[184:187], v[216:219], v[2:5]
	v_mfma_f32_16x16x32_bf16 v[54:57], v[180:183], v[196:199], v[54:57]
	v_mfma_f32_16x16x32_bf16 v[50:53], v[188:191], v[196:199], v[50:53]
	v_mfma_f32_16x16x32_bf16 v[38:41], v[180:183], v[204:207], v[38:41]
	v_mfma_f32_16x16x32_bf16 v[34:37], v[188:191], v[204:207], v[34:37]
	v_mfma_f32_16x16x32_bf16 v[22:25], v[180:183], v[212:215], v[22:25]
	v_mfma_f32_16x16x32_bf16 v[18:21], v[188:191], v[212:215], v[18:21]
	v_mfma_f32_16x16x32_bf16 v[6:9], v[180:183], v[220:223], v[6:9]
	v_mfma_f32_16x16x32_bf16 v[2:5], v[188:191], v[220:223], v[2:5]
	s_barrier
	s_add_u32 s22, s22, 0x100
	s_addc_u32 s23, s23, 0
	s_add_u32 s6, s6, 0x100
	s_addc_u32 s7, s7, 0
	s_cmp_ge_i32 s24, s14
	s_mov_b32 s8, s24
	s_cbranch_scc0 .LBB0_129
